# P3 EpiQ rope epilogue: preload the wave's 16 distinct rope-table entries once (dead A/B fragment VGPRs), the 32 steps copy instead of load+wait
# speedup vs baseline: 1.0067x; 1.0016x over previous
.LBB0_662:
	s_lshl_b32 s31, s28, 24
	v_lshl_or_b32 v130, s29, 6, v131
	s_sext_i32_i8 s62, s28
	s_lshl_b32 s30, s30, 8
	s_lshl_b32 s63, s62, 8
	s_ashr_i32 s28, s31, 24
	v_add_u32_e32 v143, s30, v130
	s_cmp_lt_i32 s28, 4
	v_lshlrev_b32_e32 v133, 2, v128
	s_mov_b64 s[28:29], -1
	v_add_u32_e32 v134, 0xffffe000, v143
	v_add_u32_e32 v128, 0xffffe010, v143
	v_add_u32_e32 v132, 0xffffe020, v143
	v_add_u32_e32 v130, 0xffffe030, v143
	s_mov_b32 s84, s34
	s_cbranch_scc1 .LBB0_664
	v_and_b32_e32 v135, 0xfcf, v143
	v_or_b32_e32 v145, 0x1000, v131
	v_cmp_gt_i32_e32 vcc, s33, v143
	v_bitop3_b32 v136, v133, 44, s72 bitop3:0xc8
	s_add_i32 s28, s63, s61
	v_cndmask_b32_e32 v135, v145, v135, vcc
	v_lshlrev_b32_e32 v144, 6, v135
	v_or_b32_e32 v135, v144, v136
	v_lshlrev_b32_e32 v166, 2, v135
	v_mov_b32_e32 v169, v143
	v_and_b32_e32 v170, 0xfff, v169
	v_and_b32_e32 v169, 31, v169
	v_or_b32_e32 v169, 0x1000, v169
	v_cndmask_b32_e32 v169, v169, v170, vcc
	v_lshl_or_b32 v169, v169, 6, v136
	v_lshlrev_b32_e32 v169, 2, v169
	global_load_dwordx4 v[172:175], v169, s[16:17]
	global_load_dwordx4 v[176:179], v169, s[16:17] offset:64
	v_add_u32_e32 v169, 0x10, v143
	v_and_b32_e32 v170, 0xfff, v169
	v_and_b32_e32 v169, 31, v169
	v_or_b32_e32 v169, 0x1000, v169
	v_cndmask_b32_e32 v169, v169, v170, vcc
	v_lshl_or_b32 v169, v169, 6, v136
	v_lshlrev_b32_e32 v169, 2, v169
	global_load_dwordx4 v[180:183], v169, s[16:17]
	global_load_dwordx4 v[184:187], v169, s[16:17] offset:64
	v_add_u32_e32 v169, 0x20, v143
	v_and_b32_e32 v170, 0xfff, v169
	v_and_b32_e32 v169, 31, v169
	v_or_b32_e32 v169, 0x1000, v169
	v_cndmask_b32_e32 v169, v169, v170, vcc
	v_lshl_or_b32 v169, v169, 6, v136
	v_lshlrev_b32_e32 v169, 2, v169
	global_load_dwordx4 v[188:191], v169, s[16:17]
	global_load_dwordx4 v[192:195], v169, s[16:17] offset:64
	v_add_u32_e32 v169, 0x30, v143
	v_and_b32_e32 v170, 0xfff, v169
	v_and_b32_e32 v169, 31, v169
	v_or_b32_e32 v169, 0x1000, v169
	v_cndmask_b32_e32 v169, v169, v170, vcc
	v_lshl_or_b32 v169, v169, 6, v136
	v_lshlrev_b32_e32 v169, 2, v169
	global_load_dwordx4 v[196:199], v169, s[16:17]
	global_load_dwordx4 v[200:203], v169, s[16:17] offset:64
	v_add_u32_e32 v169, 0x80, v143
	v_and_b32_e32 v170, 0xfff, v169
	v_and_b32_e32 v169, 31, v169
	v_or_b32_e32 v169, 0x1000, v169
	v_cndmask_b32_e32 v169, v169, v170, vcc
	v_lshl_or_b32 v169, v169, 6, v136
	v_lshlrev_b32_e32 v169, 2, v169
	global_load_dwordx4 v[204:207], v169, s[16:17]
	global_load_dwordx4 v[208:211], v169, s[16:17] offset:64
	v_add_u32_e32 v169, 0x90, v143
	v_and_b32_e32 v170, 0xfff, v169
	v_and_b32_e32 v169, 31, v169
	v_or_b32_e32 v169, 0x1000, v169
	v_cndmask_b32_e32 v169, v169, v170, vcc
	v_lshl_or_b32 v169, v169, 6, v136
	v_lshlrev_b32_e32 v169, 2, v169
	global_load_dwordx4 v[212:215], v169, s[16:17]
	global_load_dwordx4 v[222:225], v169, s[16:17] offset:64
	v_add_u32_e32 v169, 0xa0, v143
	v_and_b32_e32 v170, 0xfff, v169
	v_and_b32_e32 v169, 31, v169
	v_or_b32_e32 v169, 0x1000, v169
	v_cndmask_b32_e32 v169, v169, v170, vcc
	v_lshl_or_b32 v169, v169, 6, v136
	v_lshlrev_b32_e32 v169, 2, v169
	global_load_dwordx4 v[226:229], v169, s[16:17]
	global_load_dwordx4 v[230:233], v169, s[16:17] offset:64
	v_add_u32_e32 v169, 0xb0, v143
	v_and_b32_e32 v170, 0xfff, v169
	v_and_b32_e32 v169, 31, v169
	v_or_b32_e32 v169, 0x1000, v169
	v_cndmask_b32_e32 v169, v169, v170, vcc
	v_lshl_or_b32 v169, v169, 6, v136
	v_lshlrev_b32_e32 v169, 2, v169
	global_load_dwordx4 v[234:237], v169, s[16:17]
	global_load_dwordx4 v[238:241], v169, s[16:17] offset:64
	s_waitcnt vmcnt(0)
	v_mov_b64_e32 v[146:147], v[172:173]
	v_mov_b64_e32 v[148:149], v[174:175]
	v_mov_b64_e32 v[140:141], s[0:1]
	s_add_i32 s30, s28, 0xfffffc00
	v_mad_i64_i32 v[156:157], s[28:29], v143, s45, v[140:141]
	v_lshrrev_b32_e32 v150, 5, v134
	v_mov_b32_e32 v151, v129
	s_ashr_i32 s29, s30, 6
	v_lshlrev_b64 v[150:151], 8, v[150:151]
	s_lshl_b32 s28, s29, 5
	v_or_b32_e32 v150, v150, v131
	s_mul_i32 s38, s29, 0xc0
	s_ashr_i32 s29, s28, 31
	v_mov_b64_e32 v[138:139], s[50:51]
	s_ashr_i32 s39, s38, 31
	v_lshl_add_u64 v[158:159], v[150:151], 0, s[28:29]
	s_lshl_b64 s[30:31], s[38:39], 1
	v_mad_u64_u32 v[160:161], s[36:37], v158, s57, v[138:139]
	v_lshl_add_u64 v[162:163], v[156:157], 0, s[30:31]
	v_mad_i32_i24 v161, v159, s57, v161
	v_lshl_add_u64 v[158:159], v[162:163], 0, s[6:7]
	v_lshl_add_u64 v[160:161], v[160:161], 0, s[22:23]
	v_cndmask_b32_e32 v159, v161, v159, vcc
	v_cndmask_b32_e32 v158, v160, v158, vcc
	v_mov_b32_e32 v154, v124
	v_mov_b32_e32 v155, v127
	v_mov_b32_e32 v152, v125
	v_mov_b32_e32 v153, v126
	v_mov_b32_e32 v137, v129
	v_or_b32_e32 v135, 16, v136
	v_or_b32_e32 v144, v144, v135
	v_lshl_add_u64 v[158:159], v[158:159], 0, v[136:137]
	v_lshlrev_b32_e32 v144, 2, v144
	s_or_b32 s36, s28, 64
	s_addk_i32 s38, 0x180
	s_ashr_i32 s37, s36, 31
	s_ashr_i32 s39, s38, 31
	v_lshl_add_u64 v[150:151], v[150:151], 0, s[36:37]
	v_lshl_add_u64 v[156:157], s[38:39], 1, v[156:157]
	v_lshl_add_u64 v[156:157], v[156:157], 0, s[6:7]
	v_pk_mul_f32 v[160:161], v[126:127], v[148:149]
	v_pk_mul_f32 v[162:163], v[124:125], v[146:147]
	v_mov_b32_e32 v164, v146
	v_mov_b32_e32 v165, v149
	v_mov_b32_e32 v146, v147
	v_mov_b32_e32 v147, v148
	v_mov_b32_e32 v148, v162
	v_mov_b32_e32 v149, v160
	v_mov_b32_e32 v160, v163
	v_pk_mul_f32 v[146:147], v[154:155], v[146:147]
	v_pk_add_f32 v[148:149], v[148:149], v[160:161] neg_lo:[0,1] neg_hi:[0,1]
	v_pk_fma_f32 v[146:147], v[152:153], v[164:165], v[146:147]
	v_pk_mul_f32 v[148:149], v[148:149], s[24:25] op_sel_hi:[1,0]
	v_pk_mul_f32 v[146:147], v[146:147], s[24:25] op_sel_hi:[1,0]
	v_cvt_pk_bf16_f32 v148, v148, v149
	v_cvt_pk_bf16_f32 v146, v146, v147
	v_mov_b32_e32 v216, v148
	v_mov_b32_e32 v217, v146
	global_store_dword v[158:159], v216, off
	global_store_dword v[158:159], v217, off offset:64
	v_mov_b64_e32 v[146:147], v[176:177]
	v_mov_b64_e32 v[148:149], v[178:179]
	v_mov_b32_e32 v154, v120
	v_mov_b32_e32 v155, v123
	v_mov_b32_e32 v152, v121
	v_mov_b32_e32 v153, v122
	v_pk_mul_f32 v[160:161], v[122:123], v[148:149]
	v_pk_mul_f32 v[162:163], v[120:121], v[146:147]
	v_mov_b32_e32 v164, v146
	v_mov_b32_e32 v165, v149
	v_mov_b32_e32 v146, v147
	v_mov_b32_e32 v147, v148
	v_mov_b32_e32 v148, v162
	v_mov_b32_e32 v149, v160
	v_mov_b32_e32 v160, v163
	v_pk_mul_f32 v[146:147], v[154:155], v[146:147]
	v_pk_add_f32 v[148:149], v[148:149], v[160:161] neg_lo:[0,1] neg_hi:[0,1]
	v_pk_fma_f32 v[146:147], v[152:153], v[164:165], v[146:147]
	v_pk_mul_f32 v[148:149], v[148:149], s[24:25] op_sel_hi:[1,0]
	v_pk_mul_f32 v[146:147], v[146:147], s[24:25] op_sel_hi:[1,0]
	v_cvt_pk_bf16_f32 v148, v148, v149
	v_cvt_pk_bf16_f32 v146, v146, v147
	v_mov_b32_e32 v216, v148
	v_mov_b32_e32 v217, v146
	global_store_dword v[158:159], v216, off offset:16
	global_store_dword v[158:159], v217, off offset:80
	v_mov_b64_e32 v[146:147], v[172:173]
	v_mov_b64_e32 v[148:149], v[174:175]
	v_mad_u64_u32 v[158:159], s[38:39], v150, s57, v[138:139]
	v_mad_i32_i24 v159, v151, s57, v159
	v_lshl_add_u64 v[150:151], v[158:159], 0, s[22:23]
	v_cndmask_b32_e32 v151, v151, v157, vcc
	v_cndmask_b32_e32 v150, v150, v156, vcc
	v_lshl_add_u64 v[156:157], v[150:151], 0, v[136:137]
	v_mov_b32_e32 v154, v116
	v_mov_b32_e32 v155, v119
	v_mov_b32_e32 v152, v117
	v_mov_b32_e32 v153, v118
	v_pk_mul_f32 v[150:151], v[118:119], v[148:149]
	v_pk_mul_f32 v[158:159], v[116:117], v[146:147]
	v_mov_b32_e32 v160, v146
	v_mov_b32_e32 v161, v149
	v_mov_b32_e32 v146, v147
	v_mov_b32_e32 v147, v148
	v_mov_b32_e32 v148, v158
	v_mov_b32_e32 v149, v150
	v_mov_b32_e32 v150, v159
	v_pk_mul_f32 v[146:147], v[154:155], v[146:147]
	v_pk_add_f32 v[148:149], v[148:149], v[150:151] neg_lo:[0,1] neg_hi:[0,1]
	v_pk_fma_f32 v[146:147], v[152:153], v[160:161], v[146:147]
	v_pk_mul_f32 v[148:149], v[148:149], s[24:25] op_sel_hi:[1,0]
	v_pk_mul_f32 v[146:147], v[146:147], s[24:25] op_sel_hi:[1,0]
	v_cvt_pk_bf16_f32 v148, v148, v149
	v_cvt_pk_bf16_f32 v146, v146, v147
	v_mov_b32_e32 v216, v148
	v_mov_b32_e32 v217, v146
	global_store_dword v[156:157], v216, off
	global_store_dword v[156:157], v217, off offset:64
	v_mov_b64_e32 v[148:149], v[176:177]
	v_mov_b64_e32 v[150:151], v[178:179]
	v_add_u32_e32 v147, 16, v143
	v_or_b32_e32 v146, 0x1010, v131
	v_and_b32_e32 v144, 0xfdf, v147
	v_cmp_gt_i32_e32 vcc, s33, v147
	v_mov_b32_e32 v154, v112
	v_mov_b32_e32 v155, v115
	v_cndmask_b32_e32 v144, v146, v144, vcc
	v_mov_b32_e32 v152, v113
	v_mov_b32_e32 v153, v114
	v_lshlrev_b32_e32 v164, 6, v144
	v_or_b32_e32 v144, v164, v136
	v_lshlrev_b32_e32 v168, 2, v144
	v_pk_mul_f32 v[158:159], v[114:115], v[150:151]
	v_pk_mul_f32 v[160:161], v[112:113], v[148:149]
	v_mov_b32_e32 v162, v148
	v_mov_b32_e32 v163, v151
	v_mov_b32_e32 v148, v149
	v_mov_b32_e32 v149, v150
	v_mov_b32_e32 v150, v160
	v_mov_b32_e32 v151, v158
	v_mov_b32_e32 v158, v161
	v_pk_mul_f32 v[148:149], v[154:155], v[148:149]
	v_pk_add_f32 v[150:151], v[150:151], v[158:159] neg_lo:[0,1] neg_hi:[0,1]
	v_pk_fma_f32 v[148:149], v[152:153], v[162:163], v[148:149]
	v_pk_mul_f32 v[150:151], v[150:151], s[24:25] op_sel_hi:[1,0]
	v_pk_mul_f32 v[148:149], v[148:149], s[24:25] op_sel_hi:[1,0]
	v_cvt_pk_bf16_f32 v144, v150, v151
	v_cvt_pk_bf16_f32 v148, v148, v149
	v_mov_b32_e32 v216, v144
	v_mov_b32_e32 v217, v148
	global_store_dword v[156:157], v216, off offset:16
	global_store_dword v[156:157], v217, off offset:80
	v_mov_b64_e32 v[148:149], v[180:181]
	v_mov_b64_e32 v[150:151], v[182:183]
	v_lshrrev_b32_e32 v152, 5, v128
	v_mov_b32_e32 v153, v129
	v_or_b32_e32 v144, 16, v131
	v_lshlrev_b64 v[152:153], 8, v[152:153]
	v_or_b32_e32 v152, v152, v144
	v_lshl_add_u64 v[160:161], v[152:153], 0, s[28:29]
	v_mad_i64_i32 v[158:159], s[38:39], v147, s45, v[140:141]
	v_mad_u64_u32 v[162:163], s[38:39], v160, s57, v[138:139]
	v_lshl_add_u64 v[158:159], v[158:159], 0, s[30:31]
	v_mad_i32_i24 v163, v161, s57, v163
	v_lshl_add_u64 v[160:161], v[158:159], 0, s[6:7]
	v_lshl_add_u64 v[162:163], v[162:163], 0, s[22:23]
	v_or_b32_e32 v147, v164, v135
	v_cndmask_b32_e32 v161, v163, v161, vcc
	v_cndmask_b32_e32 v160, v162, v160, vcc
	v_mov_b32_e32 v156, v108
	v_mov_b32_e32 v157, v111
	v_mov_b32_e32 v154, v109
	v_mov_b32_e32 v155, v110
	v_lshl_add_u64 v[160:161], v[160:161], 0, v[136:137]
	v_lshlrev_b32_e32 v147, 2, v147
	v_lshl_add_u64 v[152:153], v[152:153], 0, s[36:37]
	v_lshl_add_u64 v[158:159], v[158:159], 0, s[26:27]
	v_pk_mul_f32 v[162:163], v[110:111], v[150:151]
	v_pk_mul_f32 v[164:165], v[108:109], v[148:149]
	v_mov_b32_e32 v166, v148
	v_mov_b32_e32 v167, v151
	v_mov_b32_e32 v148, v149
	v_mov_b32_e32 v149, v150
	v_mov_b32_e32 v150, v164
	v_mov_b32_e32 v151, v162
	v_mov_b32_e32 v162, v165
	v_pk_mul_f32 v[148:149], v[156:157], v[148:149]
	v_pk_add_f32 v[150:151], v[150:151], v[162:163] neg_lo:[0,1] neg_hi:[0,1]
	v_pk_fma_f32 v[148:149], v[154:155], v[166:167], v[148:149]
	v_pk_mul_f32 v[150:151], v[150:151], s[24:25] op_sel_hi:[1,0]
	v_pk_mul_f32 v[148:149], v[148:149], s[24:25] op_sel_hi:[1,0]
	v_cvt_pk_bf16_f32 v150, v150, v151
	v_cvt_pk_bf16_f32 v148, v148, v149
	v_mov_b32_e32 v216, v150
	v_mov_b32_e32 v217, v148
	global_store_dword v[160:161], v216, off
	global_store_dword v[160:161], v217, off offset:64
	v_mov_b64_e32 v[148:149], v[184:185]
	v_mov_b64_e32 v[150:151], v[186:187]
	v_mov_b32_e32 v156, v104
	v_mov_b32_e32 v157, v107
	v_mov_b32_e32 v154, v105
	v_mov_b32_e32 v155, v106
	v_pk_mul_f32 v[162:163], v[106:107], v[150:151]
	v_pk_mul_f32 v[164:165], v[104:105], v[148:149]
	v_mov_b32_e32 v166, v148
	v_mov_b32_e32 v167, v151
	v_mov_b32_e32 v148, v149
	v_mov_b32_e32 v149, v150
	v_mov_b32_e32 v150, v164
	v_mov_b32_e32 v151, v162
	v_mov_b32_e32 v162, v165
	v_pk_mul_f32 v[148:149], v[156:157], v[148:149]
	v_pk_add_f32 v[150:151], v[150:151], v[162:163] neg_lo:[0,1] neg_hi:[0,1]
	v_pk_fma_f32 v[148:149], v[154:155], v[166:167], v[148:149]
	v_pk_mul_f32 v[150:151], v[150:151], s[24:25] op_sel_hi:[1,0]
	v_pk_mul_f32 v[148:149], v[148:149], s[24:25] op_sel_hi:[1,0]
	v_cvt_pk_bf16_f32 v150, v150, v151
	v_cvt_pk_bf16_f32 v148, v148, v149
	v_mov_b32_e32 v216, v150
	v_mov_b32_e32 v217, v148
	global_store_dword v[160:161], v216, off offset:16
	global_store_dword v[160:161], v217, off offset:80
	v_mov_b64_e32 v[148:149], v[180:181]
	v_mov_b64_e32 v[150:151], v[182:183]
	v_mad_u64_u32 v[160:161], s[38:39], v152, s57, v[138:139]
	v_mad_i32_i24 v161, v153, s57, v161
	v_lshl_add_u64 v[152:153], v[160:161], 0, s[22:23]
	v_cndmask_b32_e32 v153, v153, v159, vcc
	v_cndmask_b32_e32 v152, v152, v158, vcc
	v_mov_b32_e32 v156, v100
	v_mov_b32_e32 v157, v103
	v_mov_b32_e32 v154, v101
	v_mov_b32_e32 v155, v102
	v_lshl_add_u64 v[152:153], v[152:153], 0, v[136:137]
	v_pk_mul_f32 v[158:159], v[102:103], v[150:151]
	v_pk_mul_f32 v[160:161], v[100:101], v[148:149]
	v_mov_b32_e32 v162, v148
	v_mov_b32_e32 v163, v151
	v_mov_b32_e32 v148, v149
	v_mov_b32_e32 v149, v150
	v_mov_b32_e32 v150, v160
	v_mov_b32_e32 v151, v158
	v_mov_b32_e32 v158, v161
	v_pk_mul_f32 v[148:149], v[156:157], v[148:149]
	v_pk_add_f32 v[150:151], v[150:151], v[158:159] neg_lo:[0,1] neg_hi:[0,1]
	v_pk_fma_f32 v[148:149], v[154:155], v[162:163], v[148:149]
	v_pk_mul_f32 v[150:151], v[150:151], s[24:25] op_sel_hi:[1,0]
	v_pk_mul_f32 v[148:149], v[148:149], s[24:25] op_sel_hi:[1,0]
	v_cvt_pk_bf16_f32 v150, v150, v151
	v_cvt_pk_bf16_f32 v148, v148, v149
	v_mov_b32_e32 v216, v150
	v_mov_b32_e32 v217, v148
	global_store_dword v[152:153], v216, off
	global_store_dword v[152:153], v217, off offset:64
	v_mov_b64_e32 v[148:149], v[184:185]
	v_mov_b64_e32 v[150:151], v[186:187]
	v_add_u32_e32 v147, 32, v143
	v_and_b32_e32 v158, 0xfef, v147
	v_cmp_gt_i32_e32 vcc, s33, v147
	v_mov_b32_e32 v156, v96
	v_mov_b32_e32 v157, v99
	v_cndmask_b32_e32 v158, v145, v158, vcc
	v_lshlrev_b32_e32 v164, 6, v158
	v_or_b32_e32 v158, v164, v136
	v_lshlrev_b32_e32 v168, 2, v158
	v_mov_b32_e32 v154, v97
	v_mov_b32_e32 v155, v98
	v_pk_mul_f32 v[158:159], v[98:99], v[150:151]
	v_pk_mul_f32 v[160:161], v[96:97], v[148:149]
	v_mov_b32_e32 v162, v148
	v_mov_b32_e32 v163, v151
	v_mov_b32_e32 v148, v149
	v_mov_b32_e32 v149, v150
	v_mov_b32_e32 v150, v160
	v_mov_b32_e32 v151, v158
	v_mov_b32_e32 v158, v161
	v_pk_mul_f32 v[148:149], v[156:157], v[148:149]
	v_pk_add_f32 v[150:151], v[150:151], v[158:159] neg_lo:[0,1] neg_hi:[0,1]
	v_pk_fma_f32 v[148:149], v[154:155], v[162:163], v[148:149]
	v_pk_mul_f32 v[150:151], v[150:151], s[24:25] op_sel_hi:[1,0]
	v_pk_mul_f32 v[148:149], v[148:149], s[24:25] op_sel_hi:[1,0]
	v_cvt_pk_bf16_f32 v150, v150, v151
	v_cvt_pk_bf16_f32 v148, v148, v149
	v_mov_b32_e32 v216, v150
	v_mov_b32_e32 v217, v148
	global_store_dword v[152:153], v216, off offset:16
	global_store_dword v[152:153], v217, off offset:80
	v_mov_b64_e32 v[148:149], v[188:189]
	v_mov_b64_e32 v[150:151], v[190:191]
	v_lshrrev_b32_e32 v152, 5, v132
	v_mov_b32_e32 v153, v129
	v_lshlrev_b64 v[152:153], 8, v[152:153]
	v_or_b32_e32 v152, v152, v131
	v_lshl_add_u64 v[160:161], v[152:153], 0, s[28:29]
	v_mad_i64_i32 v[158:159], s[38:39], v147, s45, v[140:141]
	v_mad_u64_u32 v[162:163], s[38:39], v160, s57, v[138:139]
	v_lshl_add_u64 v[158:159], v[158:159], 0, s[30:31]
	v_mad_i32_i24 v163, v161, s57, v163
	v_lshl_add_u64 v[160:161], v[158:159], 0, s[6:7]
	v_lshl_add_u64 v[162:163], v[162:163], 0, s[22:23]
	v_or_b32_e32 v147, v164, v135
	v_cndmask_b32_e32 v161, v163, v161, vcc
	v_cndmask_b32_e32 v160, v162, v160, vcc
	v_mov_b32_e32 v156, v92
	v_mov_b32_e32 v157, v95
	v_mov_b32_e32 v154, v93
	v_mov_b32_e32 v155, v94
	v_lshl_add_u64 v[160:161], v[160:161], 0, v[136:137]
	v_lshlrev_b32_e32 v147, 2, v147
	v_lshl_add_u64 v[152:153], v[152:153], 0, s[36:37]
	v_lshl_add_u64 v[158:159], v[158:159], 0, s[26:27]
	v_pk_mul_f32 v[162:163], v[94:95], v[150:151]
	v_pk_mul_f32 v[164:165], v[92:93], v[148:149]
	v_mov_b32_e32 v166, v148
	v_mov_b32_e32 v167, v151
	v_mov_b32_e32 v148, v149
	v_mov_b32_e32 v149, v150
	v_mov_b32_e32 v150, v164
	v_mov_b32_e32 v151, v162
	v_mov_b32_e32 v162, v165
	v_pk_mul_f32 v[148:149], v[156:157], v[148:149]
	v_pk_add_f32 v[150:151], v[150:151], v[162:163] neg_lo:[0,1] neg_hi:[0,1]
	v_pk_fma_f32 v[148:149], v[154:155], v[166:167], v[148:149]
	v_pk_mul_f32 v[150:151], v[150:151], s[24:25] op_sel_hi:[1,0]
	v_pk_mul_f32 v[148:149], v[148:149], s[24:25] op_sel_hi:[1,0]
	v_cvt_pk_bf16_f32 v150, v150, v151
	v_cvt_pk_bf16_f32 v148, v148, v149
	v_mov_b32_e32 v216, v150
	v_mov_b32_e32 v217, v148
	global_store_dword v[160:161], v216, off
	global_store_dword v[160:161], v217, off offset:64
	v_mov_b64_e32 v[148:149], v[192:193]
	v_mov_b64_e32 v[150:151], v[194:195]
	v_mov_b32_e32 v156, v88
	v_mov_b32_e32 v157, v91
	v_mov_b32_e32 v154, v89
	v_mov_b32_e32 v155, v90
	v_pk_mul_f32 v[162:163], v[90:91], v[150:151]
	v_pk_mul_f32 v[164:165], v[88:89], v[148:149]
	v_mov_b32_e32 v166, v148
	v_mov_b32_e32 v167, v151
	v_mov_b32_e32 v148, v149
	v_mov_b32_e32 v149, v150
	v_mov_b32_e32 v150, v164
	v_mov_b32_e32 v151, v162
	v_mov_b32_e32 v162, v165
	v_pk_mul_f32 v[148:149], v[156:157], v[148:149]
	v_pk_add_f32 v[150:151], v[150:151], v[162:163] neg_lo:[0,1] neg_hi:[0,1]
	v_pk_fma_f32 v[148:149], v[154:155], v[166:167], v[148:149]
	v_pk_mul_f32 v[150:151], v[150:151], s[24:25] op_sel_hi:[1,0]
	v_pk_mul_f32 v[148:149], v[148:149], s[24:25] op_sel_hi:[1,0]
	v_cvt_pk_bf16_f32 v150, v150, v151
	v_cvt_pk_bf16_f32 v148, v148, v149
	v_mov_b32_e32 v216, v150
	v_mov_b32_e32 v217, v148
	global_store_dword v[160:161], v216, off offset:16
	global_store_dword v[160:161], v217, off offset:80
	v_mov_b64_e32 v[148:149], v[188:189]
	v_mov_b64_e32 v[150:151], v[190:191]
	v_mad_u64_u32 v[160:161], s[38:39], v152, s57, v[138:139]
	v_mad_i32_i24 v161, v153, s57, v161
	v_lshl_add_u64 v[152:153], v[160:161], 0, s[22:23]
	v_cndmask_b32_e32 v153, v153, v159, vcc
	v_cndmask_b32_e32 v152, v152, v158, vcc
	v_mov_b32_e32 v156, v84
	v_mov_b32_e32 v157, v87
	v_mov_b32_e32 v154, v85
	v_mov_b32_e32 v155, v86
	v_lshl_add_u64 v[152:153], v[152:153], 0, v[136:137]
	v_pk_mul_f32 v[158:159], v[86:87], v[150:151]
	v_pk_mul_f32 v[160:161], v[84:85], v[148:149]
	v_mov_b32_e32 v162, v148
	v_mov_b32_e32 v163, v151
	v_mov_b32_e32 v148, v149
	v_mov_b32_e32 v149, v150
	v_mov_b32_e32 v150, v160
	v_mov_b32_e32 v151, v158
	v_mov_b32_e32 v158, v161
	v_pk_mul_f32 v[148:149], v[156:157], v[148:149]
	v_pk_add_f32 v[150:151], v[150:151], v[158:159] neg_lo:[0,1] neg_hi:[0,1]
	v_pk_fma_f32 v[148:149], v[154:155], v[162:163], v[148:149]
	v_pk_mul_f32 v[150:151], v[150:151], s[24:25] op_sel_hi:[1,0]
	v_pk_mul_f32 v[148:149], v[148:149], s[24:25] op_sel_hi:[1,0]
	v_cvt_pk_bf16_f32 v150, v150, v151
	v_cvt_pk_bf16_f32 v148, v148, v149
	v_mov_b32_e32 v216, v150
	v_mov_b32_e32 v217, v148
	global_store_dword v[152:153], v216, off
	global_store_dword v[152:153], v217, off offset:64
	v_mov_b64_e32 v[148:149], v[192:193]
	v_mov_b64_e32 v[150:151], v[194:195]
	v_add_u32_e32 v147, 48, v143
	v_and_b32_e32 v158, 0xfff, v147
	v_cmp_gt_i32_e32 vcc, s33, v147
	v_mov_b32_e32 v156, v80
	v_mov_b32_e32 v157, v83
	v_cndmask_b32_e32 v158, v146, v158, vcc
	v_lshlrev_b32_e32 v164, 6, v158
	v_or_b32_e32 v158, v164, v136
	v_lshlrev_b32_e32 v168, 2, v158
	v_mov_b32_e32 v154, v81
	v_mov_b32_e32 v155, v82
	v_pk_mul_f32 v[158:159], v[82:83], v[150:151]
	v_pk_mul_f32 v[160:161], v[80:81], v[148:149]
	v_mov_b32_e32 v162, v148
	v_mov_b32_e32 v163, v151
	v_mov_b32_e32 v148, v149
	v_mov_b32_e32 v149, v150
	v_mov_b32_e32 v150, v160
	v_mov_b32_e32 v151, v158
	v_mov_b32_e32 v158, v161
	v_pk_mul_f32 v[148:149], v[156:157], v[148:149]
	v_pk_add_f32 v[150:151], v[150:151], v[158:159] neg_lo:[0,1] neg_hi:[0,1]
	v_pk_fma_f32 v[148:149], v[154:155], v[162:163], v[148:149]
	v_pk_mul_f32 v[150:151], v[150:151], s[24:25] op_sel_hi:[1,0]
	v_pk_mul_f32 v[148:149], v[148:149], s[24:25] op_sel_hi:[1,0]
	v_cvt_pk_bf16_f32 v150, v150, v151
	v_cvt_pk_bf16_f32 v148, v148, v149
	v_mov_b32_e32 v216, v150
	v_mov_b32_e32 v217, v148
	global_store_dword v[152:153], v216, off offset:16
	global_store_dword v[152:153], v217, off offset:80
	v_mov_b64_e32 v[148:149], v[196:197]
	v_mov_b64_e32 v[150:151], v[198:199]
	v_lshrrev_b32_e32 v152, 5, v130
	v_mov_b32_e32 v153, v129
	v_lshlrev_b64 v[152:153], 8, v[152:153]
	v_or_b32_e32 v152, v152, v144
	v_lshl_add_u64 v[160:161], v[152:153], 0, s[28:29]
	v_mad_i64_i32 v[158:159], s[38:39], v147, s45, v[140:141]
	v_mad_u64_u32 v[162:163], s[38:39], v160, s57, v[138:139]
	v_lshl_add_u64 v[158:159], v[158:159], 0, s[30:31]
	v_mad_i32_i24 v163, v161, s57, v163
	v_lshl_add_u64 v[160:161], v[158:159], 0, s[6:7]
	v_lshl_add_u64 v[162:163], v[162:163], 0, s[22:23]
	v_or_b32_e32 v147, v164, v135
	v_cndmask_b32_e32 v161, v163, v161, vcc
	v_cndmask_b32_e32 v160, v162, v160, vcc
	v_mov_b32_e32 v156, v76
	v_mov_b32_e32 v157, v79
	v_mov_b32_e32 v154, v77
	v_mov_b32_e32 v155, v78
	v_lshl_add_u64 v[160:161], v[160:161], 0, v[136:137]
	v_lshlrev_b32_e32 v147, 2, v147
	v_lshl_add_u64 v[152:153], v[152:153], 0, s[36:37]
	v_lshl_add_u64 v[158:159], v[158:159], 0, s[26:27]
	v_pk_mul_f32 v[162:163], v[78:79], v[150:151]
	v_pk_mul_f32 v[164:165], v[76:77], v[148:149]
	v_mov_b32_e32 v166, v148
	v_mov_b32_e32 v167, v151
	v_mov_b32_e32 v148, v149
	v_mov_b32_e32 v149, v150
	v_mov_b32_e32 v150, v164
	v_mov_b32_e32 v151, v162
	v_mov_b32_e32 v162, v165
	v_pk_mul_f32 v[148:149], v[156:157], v[148:149]
	v_pk_add_f32 v[150:151], v[150:151], v[162:163] neg_lo:[0,1] neg_hi:[0,1]
	v_pk_fma_f32 v[148:149], v[154:155], v[166:167], v[148:149]
	v_pk_mul_f32 v[150:151], v[150:151], s[24:25] op_sel_hi:[1,0]
	v_pk_mul_f32 v[148:149], v[148:149], s[24:25] op_sel_hi:[1,0]
	v_cvt_pk_bf16_f32 v150, v150, v151
	v_cvt_pk_bf16_f32 v148, v148, v149
	v_mov_b32_e32 v216, v150
	v_mov_b32_e32 v217, v148
	global_store_dword v[160:161], v216, off
	global_store_dword v[160:161], v217, off offset:64
	v_mov_b64_e32 v[148:149], v[200:201]
	v_mov_b64_e32 v[150:151], v[202:203]
	v_mov_b32_e32 v156, v72
	v_mov_b32_e32 v157, v75
	v_mov_b32_e32 v154, v73
	v_mov_b32_e32 v155, v74
	v_pk_mul_f32 v[162:163], v[74:75], v[150:151]
	v_pk_mul_f32 v[164:165], v[72:73], v[148:149]
	v_mov_b32_e32 v166, v148
	v_mov_b32_e32 v167, v151
	v_mov_b32_e32 v148, v149
	v_mov_b32_e32 v149, v150
	v_mov_b32_e32 v150, v164
	v_mov_b32_e32 v151, v162
	v_mov_b32_e32 v162, v165
	v_pk_mul_f32 v[148:149], v[156:157], v[148:149]
	v_pk_add_f32 v[150:151], v[150:151], v[162:163] neg_lo:[0,1] neg_hi:[0,1]
	v_pk_fma_f32 v[148:149], v[154:155], v[166:167], v[148:149]
	v_pk_mul_f32 v[150:151], v[150:151], s[24:25] op_sel_hi:[1,0]
	v_pk_mul_f32 v[148:149], v[148:149], s[24:25] op_sel_hi:[1,0]
	v_cvt_pk_bf16_f32 v150, v150, v151
	v_cvt_pk_bf16_f32 v148, v148, v149
	v_mov_b32_e32 v216, v150
	v_mov_b32_e32 v217, v148
	global_store_dword v[160:161], v216, off offset:16
	global_store_dword v[160:161], v217, off offset:80
	v_mov_b64_e32 v[148:149], v[196:197]
	v_mov_b64_e32 v[150:151], v[198:199]
	v_mad_u64_u32 v[160:161], s[38:39], v152, s57, v[138:139]
	v_mad_i32_i24 v161, v153, s57, v161
	v_lshl_add_u64 v[152:153], v[160:161], 0, s[22:23]
	v_cndmask_b32_e32 v153, v153, v159, vcc
	v_cndmask_b32_e32 v152, v152, v158, vcc
	v_mov_b32_e32 v156, v68
	v_mov_b32_e32 v157, v71
	v_mov_b32_e32 v154, v69
	v_mov_b32_e32 v155, v70
	v_lshl_add_u64 v[152:153], v[152:153], 0, v[136:137]
	v_pk_mul_f32 v[158:159], v[70:71], v[150:151]
	v_pk_mul_f32 v[160:161], v[68:69], v[148:149]
	v_mov_b32_e32 v162, v148
	v_mov_b32_e32 v163, v151
	v_mov_b32_e32 v148, v149
	v_mov_b32_e32 v149, v150
	v_mov_b32_e32 v150, v160
	v_mov_b32_e32 v151, v158
	v_mov_b32_e32 v158, v161
	v_pk_mul_f32 v[148:149], v[156:157], v[148:149]
	v_pk_add_f32 v[150:151], v[150:151], v[158:159] neg_lo:[0,1] neg_hi:[0,1]
	v_pk_fma_f32 v[148:149], v[154:155], v[162:163], v[148:149]
	v_pk_mul_f32 v[150:151], v[150:151], s[24:25] op_sel_hi:[1,0]
	v_pk_mul_f32 v[148:149], v[148:149], s[24:25] op_sel_hi:[1,0]
	v_cvt_pk_bf16_f32 v150, v150, v151
	v_cvt_pk_bf16_f32 v148, v148, v149
	v_mov_b32_e32 v216, v150
	v_mov_b32_e32 v217, v148
	global_store_dword v[152:153], v216, off
	global_store_dword v[152:153], v217, off offset:64
	v_mov_b64_e32 v[148:149], v[200:201]
	v_mov_b64_e32 v[150:151], v[202:203]
	v_add_u32_e32 v147, 0x80, v143
	v_and_b32_e32 v158, 0xfcf, v147
	v_cmp_gt_i32_e32 vcc, s33, v147
	v_mov_b32_e32 v156, v64
	v_mov_b32_e32 v157, v67
	v_cndmask_b32_e32 v158, v145, v158, vcc
	v_lshlrev_b32_e32 v164, 6, v158
	v_or_b32_e32 v158, v164, v136
	v_lshlrev_b32_e32 v168, 2, v158
	v_mov_b32_e32 v154, v65
	v_mov_b32_e32 v155, v66
	v_pk_mul_f32 v[158:159], v[66:67], v[150:151]
	v_pk_mul_f32 v[160:161], v[64:65], v[148:149]
	v_mov_b32_e32 v162, v148
	v_mov_b32_e32 v163, v151
	v_mov_b32_e32 v148, v149
	v_mov_b32_e32 v149, v150
	v_mov_b32_e32 v150, v160
	v_mov_b32_e32 v151, v158
	v_mov_b32_e32 v158, v161
	v_pk_mul_f32 v[148:149], v[156:157], v[148:149]
	v_pk_add_f32 v[150:151], v[150:151], v[158:159] neg_lo:[0,1] neg_hi:[0,1]
	v_pk_fma_f32 v[148:149], v[154:155], v[162:163], v[148:149]
	v_pk_mul_f32 v[150:151], v[150:151], s[24:25] op_sel_hi:[1,0]
	v_pk_mul_f32 v[148:149], v[148:149], s[24:25] op_sel_hi:[1,0]
	v_cvt_pk_bf16_f32 v150, v150, v151
	v_cvt_pk_bf16_f32 v148, v148, v149
	v_mov_b32_e32 v216, v150
	v_mov_b32_e32 v217, v148
	global_store_dword v[152:153], v216, off offset:16
	global_store_dword v[152:153], v217, off offset:80
	v_mov_b64_e32 v[148:149], v[204:205]
	v_mov_b64_e32 v[150:151], v[206:207]
	v_add_u32_e32 v152, 0xffffe080, v143
	v_mov_b32_e32 v153, v129
	v_lshrrev_b32_e32 v152, 5, v152
	v_lshlrev_b64 v[152:153], 8, v[152:153]
	v_or_b32_e32 v152, v152, v131
	v_lshl_add_u64 v[160:161], v[152:153], 0, s[28:29]
	v_mad_i64_i32 v[158:159], s[38:39], v147, s45, v[140:141]
	v_mad_u64_u32 v[162:163], s[38:39], v160, s57, v[138:139]
	v_lshl_add_u64 v[158:159], v[158:159], 0, s[30:31]
	v_mad_i32_i24 v163, v161, s57, v163
	v_lshl_add_u64 v[160:161], v[158:159], 0, s[6:7]
	v_lshl_add_u64 v[162:163], v[162:163], 0, s[22:23]
	v_or_b32_e32 v147, v164, v135
	v_cndmask_b32_e32 v161, v163, v161, vcc
	v_cndmask_b32_e32 v160, v162, v160, vcc
	v_mov_b32_e32 v156, v60
	v_mov_b32_e32 v157, v63
	v_mov_b32_e32 v154, v61
	v_mov_b32_e32 v155, v62
	v_lshl_add_u64 v[160:161], v[160:161], 0, v[136:137]
	v_lshlrev_b32_e32 v147, 2, v147
	v_lshl_add_u64 v[152:153], v[152:153], 0, s[36:37]
	v_lshl_add_u64 v[158:159], v[158:159], 0, s[26:27]
	v_pk_mul_f32 v[162:163], v[62:63], v[150:151]
	v_pk_mul_f32 v[164:165], v[60:61], v[148:149]
	v_mov_b32_e32 v166, v148
	v_mov_b32_e32 v167, v151
	v_mov_b32_e32 v148, v149
	v_mov_b32_e32 v149, v150
	v_mov_b32_e32 v150, v164
	v_mov_b32_e32 v151, v162
	v_mov_b32_e32 v162, v165
	v_pk_mul_f32 v[148:149], v[156:157], v[148:149]
	v_pk_add_f32 v[150:151], v[150:151], v[162:163] neg_lo:[0,1] neg_hi:[0,1]
	v_pk_fma_f32 v[148:149], v[154:155], v[166:167], v[148:149]
	v_pk_mul_f32 v[150:151], v[150:151], s[24:25] op_sel_hi:[1,0]
	v_pk_mul_f32 v[148:149], v[148:149], s[24:25] op_sel_hi:[1,0]
	v_cvt_pk_bf16_f32 v150, v150, v151
	v_cvt_pk_bf16_f32 v148, v148, v149
	v_mov_b32_e32 v216, v150
	v_mov_b32_e32 v217, v148
	global_store_dword v[160:161], v216, off
	global_store_dword v[160:161], v217, off offset:64
	v_mov_b64_e32 v[148:149], v[208:209]
	v_mov_b64_e32 v[150:151], v[210:211]
	v_mov_b32_e32 v156, v56
	v_mov_b32_e32 v157, v59
	v_mov_b32_e32 v154, v57
	v_mov_b32_e32 v155, v58
	v_pk_mul_f32 v[162:163], v[58:59], v[150:151]
	v_pk_mul_f32 v[164:165], v[56:57], v[148:149]
	v_mov_b32_e32 v166, v148
	v_mov_b32_e32 v167, v151
	v_mov_b32_e32 v148, v149
	v_mov_b32_e32 v149, v150
	v_mov_b32_e32 v150, v164
	v_mov_b32_e32 v151, v162
	v_mov_b32_e32 v162, v165
	v_pk_mul_f32 v[148:149], v[156:157], v[148:149]
	v_pk_add_f32 v[150:151], v[150:151], v[162:163] neg_lo:[0,1] neg_hi:[0,1]
	v_pk_fma_f32 v[148:149], v[154:155], v[166:167], v[148:149]
	v_pk_mul_f32 v[150:151], v[150:151], s[24:25] op_sel_hi:[1,0]
	v_pk_mul_f32 v[148:149], v[148:149], s[24:25] op_sel_hi:[1,0]
	v_cvt_pk_bf16_f32 v150, v150, v151
	v_cvt_pk_bf16_f32 v148, v148, v149
	v_mov_b32_e32 v216, v150
	v_mov_b32_e32 v217, v148
	global_store_dword v[160:161], v216, off offset:16
	global_store_dword v[160:161], v217, off offset:80
	v_mov_b64_e32 v[148:149], v[204:205]
	v_mov_b64_e32 v[150:151], v[206:207]
	v_mad_u64_u32 v[160:161], s[38:39], v152, s57, v[138:139]
	v_mad_i32_i24 v161, v153, s57, v161
	v_lshl_add_u64 v[152:153], v[160:161], 0, s[22:23]
	v_cndmask_b32_e32 v153, v153, v159, vcc
	v_cndmask_b32_e32 v152, v152, v158, vcc
	v_mov_b32_e32 v156, v52
	v_mov_b32_e32 v157, v55
	v_mov_b32_e32 v154, v53
	v_mov_b32_e32 v155, v54
	v_lshl_add_u64 v[152:153], v[152:153], 0, v[136:137]
	v_pk_mul_f32 v[158:159], v[54:55], v[150:151]
	v_pk_mul_f32 v[160:161], v[52:53], v[148:149]
	v_mov_b32_e32 v162, v148
	v_mov_b32_e32 v163, v151
	v_mov_b32_e32 v148, v149
	v_mov_b32_e32 v149, v150
	v_mov_b32_e32 v150, v160
	v_mov_b32_e32 v151, v158
	v_mov_b32_e32 v158, v161
	v_pk_mul_f32 v[148:149], v[156:157], v[148:149]
	v_pk_add_f32 v[150:151], v[150:151], v[158:159] neg_lo:[0,1] neg_hi:[0,1]
	v_pk_fma_f32 v[148:149], v[154:155], v[162:163], v[148:149]
	v_pk_mul_f32 v[150:151], v[150:151], s[24:25] op_sel_hi:[1,0]
	v_pk_mul_f32 v[148:149], v[148:149], s[24:25] op_sel_hi:[1,0]
	v_cvt_pk_bf16_f32 v150, v150, v151
	v_cvt_pk_bf16_f32 v148, v148, v149
	v_mov_b32_e32 v216, v150
	v_mov_b32_e32 v217, v148
	global_store_dword v[152:153], v216, off
	global_store_dword v[152:153], v217, off offset:64
	v_mov_b64_e32 v[148:149], v[208:209]
	v_mov_b64_e32 v[150:151], v[210:211]
	v_add_u32_e32 v147, 0x90, v143
	v_and_b32_e32 v158, 0xfdf, v147
	v_cmp_gt_i32_e32 vcc, s33, v147
	v_mov_b32_e32 v156, v48
	v_mov_b32_e32 v157, v51
	v_cndmask_b32_e32 v158, v146, v158, vcc
	v_lshlrev_b32_e32 v164, 6, v158
	v_or_b32_e32 v158, v164, v136
	v_lshlrev_b32_e32 v168, 2, v158
	v_mov_b32_e32 v154, v49
	v_mov_b32_e32 v155, v50
	v_pk_mul_f32 v[158:159], v[50:51], v[150:151]
	v_pk_mul_f32 v[160:161], v[48:49], v[148:149]
	v_mov_b32_e32 v162, v148
	v_mov_b32_e32 v163, v151
	v_mov_b32_e32 v148, v149
	v_mov_b32_e32 v149, v150
	v_mov_b32_e32 v150, v160
	v_mov_b32_e32 v151, v158
	v_mov_b32_e32 v158, v161
	v_pk_mul_f32 v[148:149], v[156:157], v[148:149]
	v_pk_add_f32 v[150:151], v[150:151], v[158:159] neg_lo:[0,1] neg_hi:[0,1]
	v_pk_fma_f32 v[148:149], v[154:155], v[162:163], v[148:149]
	v_pk_mul_f32 v[150:151], v[150:151], s[24:25] op_sel_hi:[1,0]
	v_pk_mul_f32 v[148:149], v[148:149], s[24:25] op_sel_hi:[1,0]
	v_cvt_pk_bf16_f32 v150, v150, v151
	v_cvt_pk_bf16_f32 v148, v148, v149
	v_mov_b32_e32 v216, v150
	v_mov_b32_e32 v217, v148
	global_store_dword v[152:153], v216, off offset:16
	global_store_dword v[152:153], v217, off offset:80
	v_mov_b64_e32 v[148:149], v[212:213]
	v_mov_b64_e32 v[150:151], v[214:215]
	v_add_u32_e32 v152, 0xffffe090, v143
	v_mov_b32_e32 v153, v129
	v_lshrrev_b32_e32 v152, 5, v152
	v_lshlrev_b64 v[152:153], 8, v[152:153]
	v_or_b32_e32 v152, v152, v144
	v_lshl_add_u64 v[160:161], v[152:153], 0, s[28:29]
	v_mad_i64_i32 v[158:159], s[38:39], v147, s45, v[140:141]
	v_mad_u64_u32 v[162:163], s[38:39], v160, s57, v[138:139]
	v_lshl_add_u64 v[158:159], v[158:159], 0, s[30:31]
	v_mad_i32_i24 v163, v161, s57, v163
	v_lshl_add_u64 v[160:161], v[158:159], 0, s[6:7]
	v_lshl_add_u64 v[162:163], v[162:163], 0, s[22:23]
	v_or_b32_e32 v147, v164, v135
	v_cndmask_b32_e32 v161, v163, v161, vcc
	v_cndmask_b32_e32 v160, v162, v160, vcc
	v_mov_b32_e32 v156, v44
	v_mov_b32_e32 v157, v47
	v_mov_b32_e32 v154, v45
	v_mov_b32_e32 v155, v46
	v_lshl_add_u64 v[160:161], v[160:161], 0, v[136:137]
	v_lshlrev_b32_e32 v147, 2, v147
	v_lshl_add_u64 v[152:153], v[152:153], 0, s[36:37]
	v_lshl_add_u64 v[158:159], v[158:159], 0, s[26:27]
	v_pk_mul_f32 v[162:163], v[46:47], v[150:151]
	v_pk_mul_f32 v[164:165], v[44:45], v[148:149]
	v_mov_b32_e32 v166, v148
	v_mov_b32_e32 v167, v151
	v_mov_b32_e32 v148, v149
	v_mov_b32_e32 v149, v150
	v_mov_b32_e32 v150, v164
	v_mov_b32_e32 v151, v162
	v_mov_b32_e32 v162, v165
	v_pk_mul_f32 v[148:149], v[156:157], v[148:149]
	v_pk_add_f32 v[150:151], v[150:151], v[162:163] neg_lo:[0,1] neg_hi:[0,1]
	v_pk_fma_f32 v[148:149], v[154:155], v[166:167], v[148:149]
	v_pk_mul_f32 v[150:151], v[150:151], s[24:25] op_sel_hi:[1,0]
	v_pk_mul_f32 v[148:149], v[148:149], s[24:25] op_sel_hi:[1,0]
	v_cvt_pk_bf16_f32 v150, v150, v151
	v_cvt_pk_bf16_f32 v148, v148, v149
	v_mov_b32_e32 v216, v150
	v_mov_b32_e32 v217, v148
	global_store_dword v[160:161], v216, off
	global_store_dword v[160:161], v217, off offset:64
	v_mov_b64_e32 v[148:149], v[222:223]
	v_mov_b64_e32 v[150:151], v[224:225]
	v_mov_b32_e32 v156, v40
	v_mov_b32_e32 v157, v43
	v_mov_b32_e32 v154, v41
	v_mov_b32_e32 v155, v42
	v_pk_mul_f32 v[162:163], v[42:43], v[150:151]
	v_pk_mul_f32 v[164:165], v[40:41], v[148:149]
	v_mov_b32_e32 v166, v148
	v_mov_b32_e32 v167, v151
	v_mov_b32_e32 v148, v149
	v_mov_b32_e32 v149, v150
	v_mov_b32_e32 v150, v164
	v_mov_b32_e32 v151, v162
	v_mov_b32_e32 v162, v165
	v_pk_mul_f32 v[148:149], v[156:157], v[148:149]
	v_pk_add_f32 v[150:151], v[150:151], v[162:163] neg_lo:[0,1] neg_hi:[0,1]
	v_pk_fma_f32 v[148:149], v[154:155], v[166:167], v[148:149]
	v_pk_mul_f32 v[150:151], v[150:151], s[24:25] op_sel_hi:[1,0]
	v_pk_mul_f32 v[148:149], v[148:149], s[24:25] op_sel_hi:[1,0]
	v_cvt_pk_bf16_f32 v150, v150, v151
	v_cvt_pk_bf16_f32 v148, v148, v149
	v_mov_b32_e32 v216, v150
	v_mov_b32_e32 v217, v148
	global_store_dword v[160:161], v216, off offset:16
	global_store_dword v[160:161], v217, off offset:80
	v_mov_b64_e32 v[148:149], v[212:213]
	v_mov_b64_e32 v[150:151], v[214:215]
	v_mad_u64_u32 v[160:161], s[38:39], v152, s57, v[138:139]
	v_mad_i32_i24 v161, v153, s57, v161
	v_lshl_add_u64 v[152:153], v[160:161], 0, s[22:23]
	v_cndmask_b32_e32 v153, v153, v159, vcc
	v_cndmask_b32_e32 v152, v152, v158, vcc
	v_mov_b32_e32 v156, v36
	v_mov_b32_e32 v157, v39
	v_mov_b32_e32 v154, v37
	v_mov_b32_e32 v155, v38
	v_lshl_add_u64 v[152:153], v[152:153], 0, v[136:137]
	v_pk_mul_f32 v[158:159], v[38:39], v[150:151]
	v_pk_mul_f32 v[160:161], v[36:37], v[148:149]
	v_mov_b32_e32 v162, v148
	v_mov_b32_e32 v163, v151
	v_mov_b32_e32 v148, v149
	v_mov_b32_e32 v149, v150
	v_mov_b32_e32 v150, v160
	v_mov_b32_e32 v151, v158
	v_mov_b32_e32 v158, v161
	v_pk_mul_f32 v[148:149], v[156:157], v[148:149]
	v_pk_add_f32 v[150:151], v[150:151], v[158:159] neg_lo:[0,1] neg_hi:[0,1]
	v_pk_fma_f32 v[148:149], v[154:155], v[162:163], v[148:149]
	v_pk_mul_f32 v[150:151], v[150:151], s[24:25] op_sel_hi:[1,0]
	v_pk_mul_f32 v[148:149], v[148:149], s[24:25] op_sel_hi:[1,0]
	v_cvt_pk_bf16_f32 v150, v150, v151
	v_cvt_pk_bf16_f32 v148, v148, v149
	v_mov_b32_e32 v216, v150
	v_mov_b32_e32 v217, v148
	global_store_dword v[152:153], v216, off
	global_store_dword v[152:153], v217, off offset:64
	v_mov_b64_e32 v[148:149], v[222:223]
	v_mov_b64_e32 v[150:151], v[224:225]
	v_add_u32_e32 v147, 0xa0, v143
	v_and_b32_e32 v158, 0xfef, v147
	v_cmp_gt_i32_e32 vcc, s33, v147
	v_mov_b32_e32 v156, v32
	v_mov_b32_e32 v157, v35
	v_cndmask_b32_e32 v145, v145, v158, vcc
	v_lshlrev_b32_e32 v145, 6, v145
	v_or_b32_e32 v158, v145, v136
	v_lshlrev_b32_e32 v168, 2, v158
	v_mov_b32_e32 v154, v33
	v_mov_b32_e32 v155, v34
	v_pk_mul_f32 v[158:159], v[34:35], v[150:151]
	v_pk_mul_f32 v[160:161], v[32:33], v[148:149]
	v_mov_b32_e32 v162, v148
	v_mov_b32_e32 v163, v151
	v_mov_b32_e32 v148, v149
	v_mov_b32_e32 v149, v150
	v_mov_b32_e32 v150, v160
	v_mov_b32_e32 v151, v158
	v_mov_b32_e32 v158, v161
	v_pk_mul_f32 v[148:149], v[156:157], v[148:149]
	v_pk_add_f32 v[150:151], v[150:151], v[158:159] neg_lo:[0,1] neg_hi:[0,1]
	v_pk_fma_f32 v[148:149], v[154:155], v[162:163], v[148:149]
	v_pk_mul_f32 v[150:151], v[150:151], s[24:25] op_sel_hi:[1,0]
	v_pk_mul_f32 v[148:149], v[148:149], s[24:25] op_sel_hi:[1,0]
	v_cvt_pk_bf16_f32 v150, v150, v151
	v_cvt_pk_bf16_f32 v148, v148, v149
	v_mov_b32_e32 v216, v150
	v_mov_b32_e32 v217, v148
	global_store_dword v[152:153], v216, off offset:16
	global_store_dword v[152:153], v217, off offset:80
	v_mov_b64_e32 v[148:149], v[226:227]
	v_mov_b64_e32 v[150:151], v[228:229]
	v_add_u32_e32 v152, 0xffffe0a0, v143
	v_mov_b32_e32 v153, v129
	v_lshrrev_b32_e32 v152, 5, v152
	v_lshlrev_b64 v[152:153], 8, v[152:153]
	v_or_b32_e32 v152, v152, v131
	v_lshl_add_u64 v[160:161], v[152:153], 0, s[28:29]
	v_mad_i64_i32 v[158:159], s[38:39], v147, s45, v[140:141]
	v_mad_u64_u32 v[162:163], s[38:39], v160, s57, v[138:139]
	v_lshl_add_u64 v[158:159], v[158:159], 0, s[30:31]
	v_mad_i32_i24 v163, v161, s57, v163
	v_lshl_add_u64 v[160:161], v[158:159], 0, s[6:7]
	v_lshl_add_u64 v[162:163], v[162:163], 0, s[22:23]
	v_cndmask_b32_e32 v161, v163, v161, vcc
	v_cndmask_b32_e32 v160, v162, v160, vcc
	v_mov_b32_e32 v156, v28
	v_mov_b32_e32 v157, v31
	v_mov_b32_e32 v154, v29
	v_mov_b32_e32 v155, v30
	v_or_b32_e32 v131, v145, v135
	v_lshl_add_u64 v[160:161], v[160:161], 0, v[136:137]
	v_lshlrev_b32_e32 v131, 2, v131
	v_lshl_add_u64 v[152:153], v[152:153], 0, s[36:37]
	v_lshl_add_u64 v[158:159], v[158:159], 0, s[26:27]
	v_pk_mul_f32 v[162:163], v[30:31], v[150:151]
	v_pk_mul_f32 v[164:165], v[28:29], v[148:149]
	v_mov_b32_e32 v166, v148
	v_mov_b32_e32 v167, v151
	v_mov_b32_e32 v148, v149
	v_mov_b32_e32 v149, v150
	v_mov_b32_e32 v150, v164
	v_mov_b32_e32 v151, v162
	v_mov_b32_e32 v162, v165
	v_pk_mul_f32 v[148:149], v[156:157], v[148:149]
	v_pk_add_f32 v[150:151], v[150:151], v[162:163] neg_lo:[0,1] neg_hi:[0,1]
	v_pk_fma_f32 v[148:149], v[154:155], v[166:167], v[148:149]
	v_pk_mul_f32 v[150:151], v[150:151], s[24:25] op_sel_hi:[1,0]
	v_pk_mul_f32 v[148:149], v[148:149], s[24:25] op_sel_hi:[1,0]
	v_cvt_pk_bf16_f32 v145, v150, v151
	v_cvt_pk_bf16_f32 v147, v148, v149
	v_mov_b32_e32 v216, v145
	v_mov_b32_e32 v217, v147
	global_store_dword v[160:161], v216, off
	global_store_dword v[160:161], v217, off offset:64
	v_mov_b64_e32 v[148:149], v[230:231]
	v_mov_b64_e32 v[150:151], v[232:233]
	v_mov_b32_e32 v156, v24
	v_mov_b32_e32 v157, v27
	v_mov_b32_e32 v154, v25
	v_mov_b32_e32 v155, v26
	v_pk_mul_f32 v[162:163], v[26:27], v[150:151]
	v_pk_mul_f32 v[164:165], v[24:25], v[148:149]
	v_mov_b32_e32 v166, v148
	v_mov_b32_e32 v167, v151
	v_mov_b32_e32 v148, v149
	v_mov_b32_e32 v149, v150
	v_mov_b32_e32 v150, v164
	v_mov_b32_e32 v151, v162
	v_mov_b32_e32 v162, v165
	v_pk_mul_f32 v[148:149], v[156:157], v[148:149]
	v_pk_add_f32 v[150:151], v[150:151], v[162:163] neg_lo:[0,1] neg_hi:[0,1]
	v_pk_fma_f32 v[148:149], v[154:155], v[166:167], v[148:149]
	v_pk_mul_f32 v[150:151], v[150:151], s[24:25] op_sel_hi:[1,0]
	v_pk_mul_f32 v[148:149], v[148:149], s[24:25] op_sel_hi:[1,0]
	v_cvt_pk_bf16_f32 v145, v150, v151
	v_cvt_pk_bf16_f32 v147, v148, v149
	v_mov_b32_e32 v216, v145
	v_mov_b32_e32 v217, v147
	global_store_dword v[160:161], v216, off offset:16
	global_store_dword v[160:161], v217, off offset:80
	v_mov_b64_e32 v[148:149], v[226:227]
	v_mov_b64_e32 v[150:151], v[228:229]
	v_mad_u64_u32 v[160:161], s[38:39], v152, s57, v[138:139]
	v_mad_i32_i24 v161, v153, s57, v161
	v_lshl_add_u64 v[152:153], v[160:161], 0, s[22:23]
	v_cndmask_b32_e32 v153, v153, v159, vcc
	v_cndmask_b32_e32 v152, v152, v158, vcc
	v_mov_b32_e32 v156, v20
	v_mov_b32_e32 v157, v23
	v_mov_b32_e32 v154, v21
	v_mov_b32_e32 v155, v22
	v_lshl_add_u64 v[152:153], v[152:153], 0, v[136:137]
	v_pk_mul_f32 v[158:159], v[22:23], v[150:151]
	v_pk_mul_f32 v[160:161], v[20:21], v[148:149]
	v_mov_b32_e32 v162, v148
	v_mov_b32_e32 v163, v151
	v_mov_b32_e32 v148, v149
	v_mov_b32_e32 v149, v150
	v_mov_b32_e32 v150, v160
	v_mov_b32_e32 v151, v158
	v_mov_b32_e32 v158, v161
	v_pk_mul_f32 v[148:149], v[156:157], v[148:149]
	v_pk_add_f32 v[150:151], v[150:151], v[158:159] neg_lo:[0,1] neg_hi:[0,1]
	v_pk_fma_f32 v[148:149], v[154:155], v[162:163], v[148:149]
	v_pk_mul_f32 v[150:151], v[150:151], s[24:25] op_sel_hi:[1,0]
	v_pk_mul_f32 v[148:149], v[148:149], s[24:25] op_sel_hi:[1,0]
	v_cvt_pk_bf16_f32 v145, v150, v151
	v_cvt_pk_bf16_f32 v147, v148, v149
	v_mov_b32_e32 v216, v145
	v_mov_b32_e32 v217, v147
	global_store_dword v[152:153], v216, off
	global_store_dword v[152:153], v217, off offset:64
	v_mov_b64_e32 v[148:149], v[230:231]
	v_mov_b64_e32 v[150:151], v[232:233]
	v_add_u32_e32 v131, 0xb0, v143
	v_and_b32_e32 v145, 0xfff, v131
	v_cmp_gt_i32_e32 vcc, s33, v131
	v_mov_b32_e32 v156, v16
	v_mov_b32_e32 v157, v19
	v_cndmask_b32_e32 v145, v146, v145, vcc
	v_lshlrev_b32_e32 v145, 6, v145
	v_or_b32_e32 v146, v145, v136
	v_lshlrev_b32_e32 v162, 2, v146
	v_mov_b32_e32 v154, v17
	v_mov_b32_e32 v155, v18
	v_mad_i64_i32 v[140:141], s[38:39], v131, s45, v[140:141]
	v_or_b32_e32 v131, v145, v135
	v_lshl_add_u64 v[140:141], v[140:141], 0, s[30:31]
	v_lshlrev_b32_e32 v131, 2, v131
	v_pk_mul_f32 v[146:147], v[18:19], v[150:151]
	v_pk_mul_f32 v[158:159], v[16:17], v[148:149]
	v_mov_b32_e32 v160, v148
	v_mov_b32_e32 v161, v151
	v_mov_b32_e32 v148, v149
	v_mov_b32_e32 v149, v150
	v_mov_b32_e32 v150, v158
	v_mov_b32_e32 v151, v146
	v_mov_b32_e32 v146, v159
	v_pk_mul_f32 v[148:149], v[156:157], v[148:149]
	v_pk_add_f32 v[146:147], v[150:151], v[146:147] neg_lo:[0,1] neg_hi:[0,1]
	v_pk_fma_f32 v[148:149], v[154:155], v[160:161], v[148:149]
	v_pk_mul_f32 v[146:147], v[146:147], s[24:25] op_sel_hi:[1,0]
	v_pk_mul_f32 v[148:149], v[148:149], s[24:25] op_sel_hi:[1,0]
	v_cvt_pk_bf16_f32 v146, v146, v147
	v_cvt_pk_bf16_f32 v147, v148, v149
	v_mov_b32_e32 v216, v146
	v_mov_b32_e32 v217, v147
	global_store_dword v[152:153], v216, off offset:16
	global_store_dword v[152:153], v217, off offset:80
	v_mov_b64_e32 v[146:147], v[234:235]
	v_mov_b64_e32 v[148:149], v[236:237]
	v_add_u32_e32 v150, 0xffffe0b0, v143
	v_mov_b32_e32 v151, v129
	v_lshrrev_b32_e32 v150, 5, v150
	v_lshlrev_b64 v[150:151], 8, v[150:151]
	v_or_b32_e32 v150, v150, v144
	v_lshl_add_u64 v[144:145], v[150:151], 0, s[28:29]
	v_mad_u64_u32 v[156:157], s[28:29], v144, s57, v[138:139]
	v_mad_i32_i24 v157, v145, s57, v157
	v_lshl_add_u64 v[144:145], v[140:141], 0, s[6:7]
	v_lshl_add_u64 v[156:157], v[156:157], 0, s[22:23]
	v_cndmask_b32_e32 v145, v157, v145, vcc
	v_cndmask_b32_e32 v144, v156, v144, vcc
	v_lshl_add_u64 v[156:157], v[144:145], 0, v[136:137]
	v_mov_b32_e32 v154, v12
	v_mov_b32_e32 v155, v15
	v_mov_b32_e32 v152, v13
	v_mov_b32_e32 v153, v14
	v_lshl_add_u64 v[150:151], v[150:151], 0, s[36:37]
	v_mad_u64_u32 v[138:139], s[28:29], v150, s57, v[138:139]
	v_mad_i32_i24 v139, v151, s57, v139
	v_lshl_add_u64 v[140:141], v[140:141], 0, s[26:27]
	v_lshl_add_u64 v[138:139], v[138:139], 0, s[22:23]
	v_cndmask_b32_e32 v139, v139, v141, vcc
	v_cndmask_b32_e32 v138, v138, v140, vcc
	v_lshl_add_u64 v[140:141], v[138:139], 0, v[136:137]
	v_pk_mul_f32 v[144:145], v[14:15], v[148:149]
	v_pk_mul_f32 v[158:159], v[12:13], v[146:147]
	v_mov_b32_e32 v160, v146
	v_mov_b32_e32 v161, v149
	v_mov_b32_e32 v146, v147
	v_mov_b32_e32 v147, v148
	v_mov_b32_e32 v148, v158
	v_mov_b32_e32 v149, v144
	v_mov_b32_e32 v144, v159
	v_pk_mul_f32 v[146:147], v[154:155], v[146:147]
	v_pk_add_f32 v[144:145], v[148:149], v[144:145] neg_lo:[0,1] neg_hi:[0,1]
	v_pk_fma_f32 v[146:147], v[152:153], v[160:161], v[146:147]
	v_pk_mul_f32 v[144:145], v[144:145], s[24:25] op_sel_hi:[1,0]
	v_pk_mul_f32 v[146:147], v[146:147], s[24:25] op_sel_hi:[1,0]
	v_cvt_pk_bf16_f32 v135, v144, v145
	v_cvt_pk_bf16_f32 v144, v146, v147
	v_mov_b32_e32 v216, v135
	v_mov_b32_e32 v217, v144
	global_store_dword v[156:157], v216, off
	global_store_dword v[156:157], v217, off offset:64
	v_mov_b64_e32 v[144:145], v[238:239]
	v_mov_b64_e32 v[146:147], v[240:241]
	v_mov_b32_e32 v152, v8
	v_mov_b32_e32 v153, v11
	v_mov_b32_e32 v148, v9
	v_mov_b32_e32 v149, v10
	v_pk_mul_f32 v[154:155], v[10:11], v[146:147]
	v_pk_mul_f32 v[158:159], v[8:9], v[144:145]
	v_mov_b32_e32 v160, v144
	v_mov_b32_e32 v161, v147
	v_mov_b32_e32 v144, v145
	v_mov_b32_e32 v145, v146
	v_mov_b32_e32 v146, v158
	v_mov_b32_e32 v147, v154
	v_mov_b32_e32 v154, v159
	v_pk_mul_f32 v[144:145], v[152:153], v[144:145]
	v_pk_add_f32 v[146:147], v[146:147], v[154:155] neg_lo:[0,1] neg_hi:[0,1]
	v_pk_fma_f32 v[144:145], v[148:149], v[160:161], v[144:145]
	v_pk_mul_f32 v[146:147], v[146:147], s[24:25] op_sel_hi:[1,0]
	v_pk_mul_f32 v[144:145], v[144:145], s[24:25] op_sel_hi:[1,0]
	v_cvt_pk_bf16_f32 v135, v146, v147
	v_cvt_pk_bf16_f32 v144, v144, v145
	v_mov_b32_e32 v216, v135
	v_mov_b32_e32 v217, v144
	global_store_dword v[156:157], v216, off offset:16
	global_store_dword v[156:157], v217, off offset:80
	v_mov_b64_e32 v[144:145], v[234:235]
	v_mov_b64_e32 v[146:147], v[236:237]
	v_mov_b32_e32 v152, v4
	v_mov_b32_e32 v153, v7
	v_mov_b32_e32 v148, v5
	v_mov_b32_e32 v149, v6
	v_pk_mul_f32 v[136:137], v[6:7], v[146:147]
	v_pk_mul_f32 v[138:139], v[4:5], v[144:145]
	v_mov_b32_e32 v150, v144
	v_mov_b32_e32 v151, v147
	v_mov_b32_e32 v144, v145
	v_mov_b32_e32 v145, v146
	v_mov_b32_e32 v146, v138
	v_mov_b32_e32 v147, v136
	v_mov_b32_e32 v136, v139
	v_pk_mul_f32 v[138:139], v[152:153], v[144:145]
	v_pk_add_f32 v[136:137], v[146:147], v[136:137] neg_lo:[0,1] neg_hi:[0,1]
	v_pk_fma_f32 v[138:139], v[148:149], v[150:151], v[138:139]
	v_pk_mul_f32 v[136:137], v[136:137], s[24:25] op_sel_hi:[1,0]
	v_pk_mul_f32 v[138:139], v[138:139], s[24:25] op_sel_hi:[1,0]
	v_cvt_pk_bf16_f32 v135, v136, v137
	v_cvt_pk_bf16_f32 v136, v138, v139
	v_mov_b32_e32 v216, v135
	v_mov_b32_e32 v217, v136
	global_store_dword v[140:141], v216, off
	global_store_dword v[140:141], v217, off offset:64
	v_mov_b64_e32 v[136:137], v[238:239]
	v_mov_b64_e32 v[138:139], v[240:241]
	v_mov_b32_e32 v146, v0
	v_mov_b32_e32 v147, v3
	v_mov_b32_e32 v144, v1
	v_mov_b32_e32 v145, v2
	v_pk_mul_f32 v[148:149], v[2:3], v[138:139]
	v_pk_mul_f32 v[150:151], v[0:1], v[136:137]
	v_mov_b32_e32 v152, v136
	v_mov_b32_e32 v153, v139
	v_mov_b32_e32 v136, v137
	v_mov_b32_e32 v137, v138
	v_mov_b32_e32 v138, v150
	v_mov_b32_e32 v139, v148
	v_mov_b32_e32 v148, v151
	v_pk_mul_f32 v[136:137], v[146:147], v[136:137]
	v_pk_add_f32 v[138:139], v[138:139], v[148:149] neg_lo:[0,1] neg_hi:[0,1]
	v_pk_fma_f32 v[136:137], v[144:145], v[152:153], v[136:137]
	v_pk_mul_f32 v[138:139], v[138:139], s[24:25] op_sel_hi:[1,0]
	v_pk_mul_f32 v[136:137], v[136:137], s[24:25] op_sel_hi:[1,0]
	v_cvt_pk_bf16_f32 v131, v138, v139
	v_cvt_pk_bf16_f32 v135, v136, v137
	global_store_dword v[140:141], v131, off offset:16
	global_store_dword v[140:141], v135, off offset:80
	s_cbranch_execnz .LBB0_657
	s_branch .LBB0_665
